# s10 + na_odd_offset: NA odd key row reads its 16 bias values from the even row's address registers with offset:124; 32 VALU per row pair removed (16 per-use adds + 16 increments)
# speedup vs baseline: 1.0034x; 1.0034x over previous
.LBB0_298:
	s_ashr_i32 s27, s45, 7
	s_and_b64 s[16:17], s[20:21], exec
	s_cselect_b32 s16, s36, s27
	s_ashr_i32 s17, s16, 31
	s_lshl_b64 s[30:31], s[16:17], 12
	s_lshl_b32 s17, s47, 6
	s_waitcnt vmcnt(0)
	v_or_b32_e32 v0, s17, v83
	s_lshl_b32 s27, s53, 1
	v_or_b32_e32 v0, s30, v0
	v_mad_u64_u32 v[8:9], s[28:29], v0, s43, v[86:87]
	v_add_lshl_u32 v0, v109, s27, 6
	v_add_lshl_u32 v10, v110, s27, 6
	v_ashrrev_i32_e32 v1, 31, v0
	v_ashrrev_i32_e32 v11, 31, v10
	v_mad_i32_i24 v9, s31, v159, v9
	v_lshlrev_b64 v[98:99], 1, v[0:1]
	v_lshlrev_b64 v[100:101], 1, v[10:11]
	v_lshl_add_u64 v[4:5], v[8:9], 0, v[98:99]
	v_lshl_add_u64 v[8:9], v[8:9], 0, v[100:101]
	global_load_dwordx4 v[0:3], v[4:5], off offset:1024
	s_nop 0
	global_load_dwordx4 v[4:7], v[4:5], off offset:2048
	s_nop 0
	global_load_dwordx4 v[16:19], v[8:9], off offset:1024
	global_load_dwordx4 v[28:31], v[8:9], off offset:2048
	s_sub_i32 s56, s52, s47
	v_or_b32_e32 v8, s17, v106
	s_lshl_b32 s17, s51, 6
	s_add_i32 s29, s27, s37
	s_add_i32 s28, s56, 8
	s_ashr_i32 s27, s17, 31
	s_add_u32 s17, s30, s17
	v_or_b32_e32 v8, s30, v8
	s_addc_u32 s51, s31, s27
	v_or_b32_e32 v38, s17, v82
	s_lshl_b32 s27, s29, 6
	s_lshl_b32 s17, s29, 7
	v_mad_u64_u32 v[20:21], s[52:53], v8, s43, v[86:87]
	s_add_u32 s30, s60, s17
	v_mad_i32_i24 v21, s31, v159, v21
	s_addc_u32 s31, s61, 0
	v_lshl_add_u64 v[12:13], v[20:21], 0, v[98:99]
	v_lshl_add_u64 v[20:21], v[20:21], 0, v[100:101]
	v_or_b32_e32 v96, s38, v38
	v_mov_b64_e32 v[36:37], s[30:31]
	v_or_b32_e32 v94, s42, v38
	global_load_dwordx4 v[8:11], v[12:13], off offset:1024
	s_nop 0
	global_load_dwordx4 v[12:15], v[12:13], off offset:2048
	s_nop 0
	global_load_dwordx4 v[32:35], v[20:21], off offset:1024
	global_load_dwordx4 v[48:51], v[20:21], off offset:2048
	v_mad_u64_u32 v[20:21], s[30:31], v96, s43, v[36:37]
	v_mad_u64_u32 v[36:37], s[30:31], v94, s43, v[36:37]
	v_mad_i32_i24 v21, s51, v159, v21
	v_mad_i32_i24 v37, s51, v159, v37
	v_lshl_add_u64 v[24:25], v[20:21], 0, v[92:93]
	v_lshl_add_u64 v[40:41], v[36:37], 0, v[92:93]
	global_load_dwordx4 v[20:23], v[24:25], off
	s_nop 0
	global_load_dwordx4 v[24:27], v[24:25], off offset:64
	s_nop 0
	global_load_dwordx4 v[36:39], v[40:41], off
	s_nop 0
	global_load_dwordx4 v[40:43], v[40:41], off offset:64
	s_mul_i32 s17, s47, 0x7c
	s_mul_i32 s52, s48, 0xf8
	s_add_i32 s29, s56, 5
	s_add_i32 s30, s56, 6
	s_add_i32 s31, s24, 8
	s_add_i32 s48, s17, 0
	s_cmp_lt_u32 s50, 56
	s_cselect_b32 s50, s50, 56
	v_mov_b32_e32 v97, s51
	v_mov_b32_e32 v95, s51
	s_mul_hi_i32 s17, s16, 0x1400000
	s_mul_i32 s16, s16, 0x1400000
	s_mul_hi_u32 s51, s50, 0x50000
	s_mul_i32 s50, s50, 0x50000
	s_add_u32 s16, s16, s50
	s_addc_u32 s17, s17, s51
	v_lshl_add_u64 v[104:105], v[90:91], 0, s[16:17]
	s_add_i32 s16, s44, s47
	s_sub_i32 s16, s16, s49
	v_mov_b32_e32 v64, v84
	v_mov_b32_e32 v65, v84
	v_mov_b32_e32 v66, v84
	v_mov_b32_e32 v67, v84
	s_mulk_i32 s16, 0x7c
	v_mov_b32_e32 v85, v84
	v_mov_b64_e32 v[78:79], v[66:67]
	v_mov_b64_e32 v[74:75], v[66:67]
	v_mov_b64_e32 v[70:71], v[66:67]
	v_mov_b64_e32 v[60:61], v[64:65]
	v_mov_b64_e32 v[56:57], v[64:65]
	v_mov_b64_e32 v[52:53], v[64:65]
	v_mov_b64_e32 v[44:45], v[64:65]
	s_waitcnt vmcnt(11)
	ds_write_b128 v160, v[0:3]
	s_waitcnt vmcnt(10)
	ds_write_b128 v160, v[4:7] offset:8192
	s_waitcnt vmcnt(9)
	ds_write_b128 v160, v[16:19] offset:16384
	s_waitcnt vmcnt(8)
	ds_write_b128 v160, v[28:31] offset:24576
	s_waitcnt vmcnt(0)
	s_waitcnt lgkmcnt(0)
	s_barrier
	v_add_u32_e32 v177, s16, v142
	v_add_u32_e32 v178, s16, v143
	v_add_u32_e32 v179, s16, v144
	v_add_u32_e32 v180, s16, v145
	v_add_u32_e32 v181, s16, v146
	v_add_u32_e32 v182, s16, v147
	v_add_u32_e32 v183, s16, v148
	v_add_u32_e32 v184, s16, v149
	v_add_u32_e32 v185, s16, v150
	v_add_u32_e32 v186, s16, v151
	v_add_u32_e32 v187, s16, v152
	v_add_u32_e32 v188, s16, v153
	v_add_u32_e32 v189, s16, v154
	v_add_u32_e32 v190, s16, v155
	v_add_u32_e32 v191, s16, v156
	v_add_u32_e32 v192, s16, v157
	s_mov_b32 s49, 2
	v_mov_b64_e32 v[76:77], v[64:65]
	v_mov_b64_e32 v[72:73], v[64:65]
	v_mov_b64_e32 v[68:69], v[64:65]
	v_mov_b64_e32 v[62:63], v[66:67]
	v_mov_b64_e32 v[58:59], v[66:67]
	v_mov_b64_e32 v[54:55], v[66:67]
	v_mov_b64_e32 v[46:47], v[66:67]
	v_mov_b64_e32 v[102:103], v[84:85]
	s_branch .LBB0_301

.LBB0_300:
	s_add_i32 s49, s49, 2
	s_mov_b64 s[16:17], 0xa0000
	v_lshl_add_u64 v[104:105], v[104:105], 0, s[16:17]
	v_add_u32_e32 v177, 0xf8, v177
	v_add_u32_e32 v178, 0xf8, v178
	v_add_u32_e32 v179, 0xf8, v179
	v_add_u32_e32 v180, 0xf8, v180
	v_add_u32_e32 v181, 0xf8, v181
	v_add_u32_e32 v182, 0xf8, v182
	v_add_u32_e32 v183, 0xf8, v183
	v_add_u32_e32 v184, 0xf8, v184
	v_add_u32_e32 v185, 0xf8, v185
	v_add_u32_e32 v186, 0xf8, v186
	v_add_u32_e32 v187, 0xf8, v187
	v_add_u32_e32 v188, 0xf8, v188
	v_add_u32_e32 v189, 0xf8, v189
	v_add_u32_e32 v190, 0xf8, v190
	v_add_u32_e32 v191, 0xf8, v191
	s_cmp_gt_u32 s50, 7
	v_add_u32_e32 v192, 0xf8, v192
	s_cbranch_scc1 .LBB0_280

.LBB0_314:
	s_add_i32 s16, s47, s49
	s_add_i32 s51, s16, -1
	s_cmp_ge_u32 s51, s24
	s_cselect_b64 s[16:17], -1, 0
	s_cmp_lt_u32 s51, s31
	s_cselect_b64 s[52:53], -1, 0
	s_and_b64 s[16:17], s[16:17], s[52:53]
	s_andn2_b64 vcc, exec, s[16:17]
	s_cbranch_vccnz .LBB0_316
	v_add_u32_e32 v85, v118, v107
	ds_read_b128 v[194:197], v85 offset:32768
	ds_read_b128 v[202:205], v85 offset:34816
	v_add_u32_e32 v193, v118, v108
	ds_read_b128 v[198:201], v193 offset:32768
	ds_read_b128 v[206:209], v193 offset:34816
	s_waitcnt lgkmcnt(3)
	v_mfma_f32_16x16x32_bf16 v[194:197], v[194:197], v[20:23], 0
	s_waitcnt lgkmcnt(1)
	v_mfma_f32_16x16x32_bf16 v[194:197], v[198:201], v[24:27], v[194:197]
	ds_read_b32 v198, v192 offset:124
	ds_read_b32 v199, v191 offset:124
	ds_read_b32 v200, v190 offset:124
	ds_read_b32 v211, v189 offset:124
	ds_read_b32 v213, v188 offset:124
	ds_read_b32 v85, v187 offset:124
	ds_read_b32 v215, v186 offset:124
	ds_read_b32 v193, v185 offset:124
	s_waitcnt lgkmcnt(7)
	v_add_f32_e32 v194, v194, v198
	v_exp_f32_e32 v210, v194
	s_waitcnt lgkmcnt(6)
	v_add_f32_e32 v194, v195, v199
	v_exp_f32_e32 v212, v194
	s_waitcnt lgkmcnt(5)
	v_add_f32_e32 v194, v196, v200
	v_mfma_f32_16x16x32_bf16 v[198:201], v[202:205], v[20:23], 0
	v_exp_f32_e32 v214, v194
	s_waitcnt lgkmcnt(4)
	v_add_f32_e32 v194, v197, v211
	v_exp_f32_e32 v218, v194
	v_mfma_f32_16x16x32_bf16 v[194:197], v[206:209], v[24:27], v[198:201]
	v_cvt_pk_bf16_f32 v202, v210, v212
	s_nop 0
	v_cvt_pk_bf16_f32 v203, v214, v218
	s_waitcnt lgkmcnt(2)
	s_nop 3
	v_add_f32_e32 v85, v195, v85
	v_exp_f32_e32 v222, v85
	s_waitcnt lgkmcnt(1)
	v_add_f32_e32 v85, v196, v215
	v_add_f32_e32 v194, v194, v213
	v_exp_f32_e32 v224, v85
	s_waitcnt lgkmcnt(0)
	v_add_f32_e32 v85, v197, v193
	v_add_u32_e32 v193, v119, v111
	v_exp_f32_e32 v220, v194
	ds_read_b64_tr_b16 v[194:195], v193 offset:40960
	ds_read_b64_tr_b16 v[196:197], v193 offset:43008
	v_exp_f32_e32 v226, v85
	v_add_u32_e32 v85, v119, v112
	ds_read_b64_tr_b16 v[198:199], v85 offset:40960
	ds_read_b64_tr_b16 v[200:201], v85 offset:43008
	v_cvt_pk_bf16_f32 v204, v220, v222
	v_cvt_pk_bf16_f32 v205, v224, v226
	v_add_u32_e32 v85, v119, v113
	v_add_u32_e32 v193, v120, v108
	s_waitcnt lgkmcnt(2)
	v_mfma_f32_16x16x32_bf16 v[76:79], v[194:197], v[202:205], v[76:79]
	ds_read_b64_tr_b16 v[194:195], v85 offset:40960
	ds_read_b64_tr_b16 v[196:197], v85 offset:43008
	v_add_u32_e32 v85, v119, v114
	s_waitcnt lgkmcnt(2)
	v_mfma_f32_16x16x32_bf16 v[64:67], v[198:201], v[202:205], v[64:67]
	ds_read_b64_tr_b16 v[198:199], v85 offset:40960
	ds_read_b64_tr_b16 v[200:201], v85 offset:43008
	v_add_u32_e32 v85, v120, v107
	s_waitcnt lgkmcnt(2)
	v_mfma_f32_16x16x32_bf16 v[72:75], v[194:197], v[202:205], v[72:75]
	ds_read_b128 v[194:197], v85 offset:32768
	s_waitcnt lgkmcnt(1)
	v_mfma_f32_16x16x32_bf16 v[68:71], v[198:201], v[202:205], v[68:71]
	ds_read_b128 v[198:201], v85 offset:34816
	ds_read_b128 v[202:205], v193 offset:32768
	ds_read_b128 v[206:209], v193 offset:34816
	s_waitcnt lgkmcnt(3)
	v_mfma_f32_16x16x32_bf16 v[194:197], v[194:197], v[36:39], 0
	s_waitcnt lgkmcnt(1)
	v_mfma_f32_16x16x32_bf16 v[194:197], v[202:205], v[40:43], v[194:197]
	ds_read_b32 v85, v184 offset:124
	ds_read_b32 v193, v183 offset:124
	ds_read_b32 v202, v182 offset:124
	ds_read_b32 v203, v181 offset:124
	ds_read_b32 v204, v180 offset:124
	ds_read_b32 v205, v179 offset:124
	ds_read_b32 v217, v178 offset:124
	ds_read_b32 v227, v177 offset:124
	v_mfma_f32_16x16x32_bf16 v[198:201], v[198:201], v[36:39], 0
	s_waitcnt lgkmcnt(7)
	v_add_f32_e32 v85, v194, v85
	v_exp_f32_e32 v211, v85
	s_waitcnt lgkmcnt(6)
	v_add_f32_e32 v85, v195, v193
	v_exp_f32_e32 v213, v85
	s_waitcnt lgkmcnt(5)
	v_add_f32_e32 v85, v196, v202
	v_exp_f32_e32 v215, v85
	s_waitcnt lgkmcnt(4)
	v_add_f32_e32 v85, v197, v203
	v_mfma_f32_16x16x32_bf16 v[194:197], v[206:209], v[40:43], v[198:201]
	v_exp_f32_e32 v219, v85
	s_waitcnt lgkmcnt(3)
	s_nop 5
	v_add_f32_e32 v85, v194, v204
	v_exp_f32_e32 v221, v85
	s_waitcnt lgkmcnt(2)
	v_add_f32_e32 v85, v195, v205
	v_exp_f32_e32 v223, v85
	s_waitcnt lgkmcnt(1)
	v_add_f32_e32 v85, v196, v217
	v_exp_f32_e32 v225, v85
	s_waitcnt lgkmcnt(0)
	v_add_f32_e32 v85, v197, v227
	v_exp_f32_e32 v227, v85
	v_add_u32_e32 v85, v121, v111
	ds_read_b64_tr_b16 v[198:199], v85 offset:40960
	ds_read_b64_tr_b16 v[200:201], v85 offset:43008
	v_pk_add_f32 v[194:195], v[210:211], 0 op_sel_hi:[1,0]
	v_add_u32_e32 v85, v121, v112
	v_pk_add_f32 v[194:195], v[194:195], v[212:213]
	ds_read_b64_tr_b16 v[202:203], v85 offset:40960
	ds_read_b64_tr_b16 v[204:205], v85 offset:43008
	v_add_u32_e32 v85, v121, v113
	v_pk_add_f32 v[228:229], v[194:195], v[214:215]
	v_cvt_pk_bf16_f32 v194, v211, v213
	v_cvt_pk_bf16_f32 v195, v215, v219
	v_cvt_pk_bf16_f32 v196, v221, v223
	v_cvt_pk_bf16_f32 v197, v225, v227
	ds_read_b64_tr_b16 v[206:207], v85 offset:40960
	ds_read_b64_tr_b16 v[208:209], v85 offset:43008
	v_add_u32_e32 v85, v121, v114
	s_waitcnt lgkmcnt(4)
	v_mfma_f32_16x16x32_bf16 v[60:63], v[198:201], v[194:197], v[60:63]
	ds_read_b64_tr_b16 v[198:199], v85 offset:40960
	ds_read_b64_tr_b16 v[200:201], v85 offset:43008
	s_waitcnt lgkmcnt(4)
	v_mfma_f32_16x16x32_bf16 v[56:59], v[202:205], v[194:197], v[56:59]
	v_add_f32_e64 v202, v228, v218
	v_add_f32_e64 v203, v229, v219
	v_pk_add_f32 v[202:203], v[202:203], v[220:221]
	s_waitcnt lgkmcnt(2)
	v_mfma_f32_16x16x32_bf16 v[52:55], v[206:209], v[194:197], v[52:55]
	v_add_f32_e64 v202, v202, v222
	v_add_f32_e64 v203, v203, v223
	v_pk_add_f32 v[202:203], v[202:203], v[224:225]
	s_waitcnt lgkmcnt(0)
	v_mfma_f32_16x16x32_bf16 v[44:47], v[198:201], v[194:197], v[44:47]
	v_add_f32_e64 v202, v202, v226
	v_add_f32_e64 v203, v203, v227
	v_pk_add_f32 v[102:103], v[202:203], v[102:103]
